# rows phases (LN/modulate + post-LN + final LN): gamma/beta/shift/scale loads hoisted ahead of the store chain; waits recounted
# speedup vs baseline: 1.0659x; 1.0215x over previous
.LBB0_428:
	s_waitcnt vmcnt(7)
	v_add_f32_e32 v0, v33, v32
	v_add_f32_e32 v0, v34, v0
	v_add_f32_e32 v1, v37, v36
	v_add_f32_e32 v0, v35, v0
	v_add_f32_e32 v1, v38, v1
	v_add_f32_e32 v0, 0, v0
	v_add_f32_e32 v1, v39, v1
	v_add_f32_e32 v0, v1, v0
	v_add_f32_e32 v1, v41, v40
	v_add_f32_e32 v1, v42, v1
	v_add_f32_e32 v1, v43, v1
	v_add_f32_e32 v0, v1, v0
	v_add_f32_e32 v1, v45, v44
	v_add_f32_e32 v1, v46, v1
	v_add_f32_e32 v1, v47, v1
	s_waitcnt vmcnt(6)
	v_add_f32_e32 v4, v1, v0
	v_mov_b32_e32 v0, v57
	v_mov_b32_e32 v1, v49
	v_mov_b32_e32 v2, v56
	v_mov_b32_e32 v3, v48
	v_pk_add_f32 v[0:1], v[0:1], v[2:3]
	v_mov_b32_e32 v2, v58
	v_mov_b32_e32 v3, v50
	v_pk_add_f32 v[0:1], v[2:3], v[0:1]
	v_mov_b32_e32 v2, v59
	v_mov_b32_e32 v3, v51
	v_pk_add_f32 v[0:1], v[2:3], v[0:1]
	v_mov_b32_e32 v2, v60
	v_add_f32_e32 v1, v1, v4
	v_add_f32_e32 v4, v0, v1
	v_mov_b32_e32 v0, v61
	v_mov_b32_e32 v1, v53
	v_mov_b32_e32 v3, v52
	v_pk_add_f32 v[0:1], v[0:1], v[2:3]
	v_mov_b32_e32 v2, v62
	v_mov_b32_e32 v3, v54
	v_pk_add_f32 v[0:1], v[2:3], v[0:1]
	v_mov_b32_e32 v2, v63
	v_mov_b32_e32 v3, v55
	v_pk_add_f32 v[0:1], v[2:3], v[0:1]
	v_cmp_lt_i32_e32 vcc, v97, v95
	v_add_f32_e32 v1, v1, v4
	v_add_f32_e32 v0, v0, v1
	v_cndmask_b32_e32 v1, v110, v97, vcc
	v_lshlrev_b32_e32 v97, 2, v1
	v_cmp_lt_i32_e32 vcc, v99, v95
	s_movk_i32 s15, 0xfff
	s_mov_b64 s[16:17], 0x2000
	s_waitcnt lgkmcnt(0)
	v_mov_b32_e32 v1, v0
	s_nop 1
	v_permlane32_swap_b32_e32 v1, v0
	v_add_f32_e32 v0, v0, v1
	v_cndmask_b32_e32 v1, v110, v99, vcc
	v_lshlrev_b32_e32 v99, 2, v1
	v_cmp_lt_i32_e32 vcc, v101, v95
	s_waitcnt lgkmcnt(0)
	v_mov_b32_e32 v1, v0
	s_nop 1
	v_permlane16_swap_b32_e32 v1, v0
	v_add_f32_e32 v0, v0, v1
	v_cndmask_b32_e32 v1, v110, v101, vcc
	v_lshlrev_b32_e32 v101, 2, v1
	v_cmp_lt_i32_e32 vcc, v103, v95
	s_waitcnt lgkmcnt(0)
	s_nop 1
	v_add_f32_dpp v0, v0, v0 row_mirror row_mask:0xf bank_mask:0xf
	v_cndmask_b32_e32 v1, v110, v103, vcc
	v_lshlrev_b32_e32 v103, 2, v1
	v_cmp_lt_i32_e32 vcc, v105, v95
	s_waitcnt lgkmcnt(0)
	s_nop 1
	v_add_f32_dpp v0, v0, v0 row_half_mirror row_mask:0xf bank_mask:0xf
	v_cndmask_b32_e32 v1, v110, v105, vcc
	v_lshlrev_b32_e32 v105, 2, v1
	v_cmp_lt_i32_e32 vcc, v107, v95
	s_waitcnt lgkmcnt(0)
	s_nop 1
	v_add_f32_dpp v0, v0, v0 quad_perm:[2,3,0,1] row_mask:0xf bank_mask:0xf
	v_cndmask_b32_e32 v1, v110, v107, vcc
	v_lshlrev_b32_e32 v95, 2, v1
	v_cmp_lt_i32_e32 vcc, s15, v88
	v_mov_b32_e32 v107, v161
	s_movk_i32 s15, 0x1fff
	s_waitcnt lgkmcnt(0)
	s_nop 1
	v_add_f32_dpp v0, v0, v0 quad_perm:[1,0,3,2] row_mask:0xf bank_mask:0xf
	v_mul_f32_e32 v6, 0x3a000000, v0
	v_ashrrev_i32_e32 v0, 10, v65
	v_add_u32_e32 v0, 1, v0
	v_cndmask_b32_e32 v0, 0, v0, vcc
	v_add_u32_e32 v0, s11, v0
	v_mul_i32_i24_e32 v0, 0x1800, v0
	v_ashrrev_i32_e32 v1, 31, v0
	v_lshl_add_u64 v[0:1], v[0:1], 2, s[48:49]
	v_lshl_add_u64 v[2:3], v[0:1], 0, s[16:17]
	s_waitcnt vmcnt(3)
	v_lshl_add_u64 v[18:19], v[0:1], 0, v[160:161]
	v_lshl_add_u64 v[4:5], v[2:3], 0, v[160:161]
	global_load_dwordx4 v[10:13], v[18:19], off
	global_load_dwordx4 v[14:17], v[4:5], off
	s_waitcnt vmcnt(4)
	v_pk_add_f32 v[20:21], v[32:33], v[6:7] op_sel_hi:[1,0] neg_lo:[0,1] neg_hi:[0,1]
	s_waitcnt vmcnt(3)
	v_pk_add_f32 v[26:27], v[36:37], v[6:7] op_sel_hi:[1,0] neg_lo:[0,1] neg_hi:[0,1]
	v_pk_mul_f32 v[8:9], v[20:21], v[20:21]
	v_pk_add_f32 v[22:23], v[34:35], v[6:7] op_sel_hi:[1,0] neg_lo:[0,1] neg_hi:[0,1]
	s_waitcnt vmcnt(2)
	v_mov_b32_e32 v95, v161
	v_lshl_add_u64 v[204:205], v[2:3], 0, v[94:95]
	global_load_dwordx4 v[206:209], v[204:205], off
	global_load_dwordx4 v[210:213], v[18:19], off offset:1024
	v_mov_b32_e32 v97, v161
	v_lshl_add_u64 v[214:215], v[2:3], 0, v[96:97]
	global_load_dwordx4 v[216:219], v[214:215], off
	global_load_dwordx4 v[220:223], v[18:19], off offset:2048
	v_mov_b32_e32 v99, v161
	v_lshl_add_u64 v[224:225], v[2:3], 0, v[98:99]
	global_load_dwordx4 v[226:229], v[224:225], off
	global_load_dwordx4 v[230:233], v[18:19], off offset:3072
	v_mov_b32_e32 v101, v161
	v_lshl_add_u64 v[18:19], v[2:3], 0, v[100:101]
	global_load_dwordx4 v[234:237], v[18:19], off
	v_lshl_add_u64 v[238:239], v[0:1], 0, v[100:101]
	global_load_dwordx4 v[240:243], v[238:239], off
	v_mov_b32_e32 v103, v161
	v_lshl_add_u64 v[18:19], v[2:3], 0, v[102:103]
	global_load_dwordx4 v[244:247], v[18:19], off
	v_lshl_add_u64 v[248:249], v[0:1], 0, v[102:103]
	global_load_dwordx4 v[172:175], v[248:249], off
	v_mov_b32_e32 v105, v161
	v_lshl_add_u64 v[18:19], v[2:3], 0, v[104:105]
	global_load_dwordx4 v[176:179], v[18:19], off
	v_lshl_add_u64 v[180:181], v[0:1], 0, v[104:105]
	global_load_dwordx4 v[182:185], v[180:181], off
	v_lshl_add_u64 v[2:3], v[2:3], 0, v[106:107]
	global_load_dwordx4 v[142:145], v[2:3], off
	v_lshl_add_u64 v[0:1], v[0:1], 0, v[106:107]
	global_load_dwordx4 v[0:3], v[0:1], off
	v_pk_mul_f32 v[28:29], v[26:27], v[26:27]
	v_pk_add_f32 v[30:31], v[38:39], v[6:7] op_sel_hi:[1,0] neg_lo:[0,1] neg_hi:[0,1]
	v_pk_add_f32 v[34:35], v[40:41], v[6:7] op_sel_hi:[1,0] neg_lo:[0,1] neg_hi:[0,1]
	v_pk_add_f32 v[48:49], v[48:49], v[6:7] op_sel_hi:[1,0] neg_lo:[0,1] neg_hi:[0,1]
	v_pk_add_f32 v[56:57], v[56:57], v[6:7] op_sel_hi:[1,0] neg_lo:[0,1] neg_hi:[0,1]
	v_pk_mul_f32 v[24:25], v[22:23], v[22:23]
	v_pk_mul_f32 v[32:33], v[30:31], v[30:31]
	v_pk_mul_f32 v[36:37], v[34:35], v[34:35]
	v_pk_add_f32 v[38:39], v[42:43], v[6:7] op_sel_hi:[1,0] neg_lo:[0,1] neg_hi:[0,1]
	v_mov_b32_e32 v112, v57
	v_mov_b32_e32 v113, v49
	v_add_f32_e32 v28, v28, v29
	v_add_f32_e32 v8, v8, v9
	v_pk_mul_f32 v[40:41], v[38:39], v[38:39]
	v_pk_add_f32 v[50:51], v[50:51], v[6:7] op_sel_hi:[1,0] neg_lo:[0,1] neg_hi:[0,1]
	v_pk_add_f32 v[58:59], v[58:59], v[6:7] op_sel_hi:[1,0] neg_lo:[0,1] neg_hi:[0,1]
	v_mov_b32_e32 v4, v56
	v_mov_b32_e32 v5, v48
	v_pk_mul_f32 v[112:113], v[112:113], v[112:113]
	v_add_f32_e32 v28, v32, v28
	v_add_f32_e32 v8, v24, v8
	v_add_f32_e32 v9, v36, v37
	v_pk_add_f32 v[42:43], v[44:45], v[6:7] op_sel_hi:[1,0] neg_lo:[0,1] neg_hi:[0,1]
	v_pk_fma_f32 v[4:5], v[4:5], v[4:5], v[112:113]
	v_mov_b32_e32 v112, v58
	v_mov_b32_e32 v113, v50
	v_add_f32_e32 v28, v33, v28
	v_add_f32_e32 v8, v25, v8
	v_add_f32_e32 v9, v40, v9
	v_pk_mul_f32 v[44:45], v[42:43], v[42:43]
	v_pk_add_f32 v[46:47], v[46:47], v[6:7] op_sel_hi:[1,0] neg_lo:[0,1] neg_hi:[0,1]
	v_mov_b32_e32 v114, v59
	v_mov_b32_e32 v115, v51
	v_pk_fma_f32 v[4:5], v[112:113], v[112:113], v[4:5]
	v_add_f32_e32 v8, v8, v28
	v_add_f32_e32 v9, v41, v9
	v_pk_mul_f32 v[110:111], v[46:47], v[46:47]
	v_pk_fma_f32 v[112:113], v[114:115], v[114:115], v[4:5]
	v_pk_add_f32 v[52:53], v[52:53], v[6:7] op_sel_hi:[1,0] neg_lo:[0,1] neg_hi:[0,1]
	v_pk_add_f32 v[4:5], v[60:61], v[6:7] op_sel_hi:[1,0] neg_lo:[0,1] neg_hi:[0,1]
	v_add_f32_e32 v8, v9, v8
	v_add_f32_e32 v9, v44, v45
	v_pk_add_f32 v[54:55], v[54:55], v[6:7] op_sel_hi:[1,0] neg_lo:[0,1] neg_hi:[0,1]
	v_pk_add_f32 v[6:7], v[62:63], v[6:7] op_sel_hi:[1,0] neg_lo:[0,1] neg_hi:[0,1]
	v_mov_b32_e32 v62, v5
	v_mov_b32_e32 v63, v53
	v_add_f32_e32 v9, v110, v9
	v_mov_b32_e32 v60, v4
	v_mov_b32_e32 v61, v52
	v_pk_mul_f32 v[62:63], v[62:63], v[62:63]
	v_add_f32_e32 v9, v111, v9
	v_pk_fma_f32 v[60:61], v[60:61], v[60:61], v[62:63]
	v_mov_b32_e32 v62, v6
	v_mov_b32_e32 v63, v54
	v_add_f32_e32 v8, v9, v8
	v_mov_b32_e32 v114, v7
	v_mov_b32_e32 v115, v55
	v_pk_fma_f32 v[60:61], v[62:63], v[62:63], v[60:61]
	v_add_f32_e32 v8, v113, v8
	v_pk_fma_f32 v[60:61], v[114:115], v[114:115], v[60:61]
	v_add_f32_e32 v8, v112, v8
	v_add_f32_e32 v8, v61, v8
	v_add_f32_e32 v8, v60, v8
	s_nop 0
	v_readlane_b32 s16, v251, 22
	v_readlane_b32 s17, v251, 23
	s_waitcnt lgkmcnt(0)
	v_mov_b32_e32 v9, v8
	s_nop 1
	v_permlane32_swap_b32_e32 v9, v8
	v_add_f32_e32 v8, v8, v9
	s_nop 0
	v_lshl_add_u64 v[90:91], v[90:91], 0, s[16:17]
	v_readlane_b32 s16, v251, 26
	v_readlane_b32 s17, v251, 27
	s_waitcnt lgkmcnt(0)
	v_mov_b32_e32 v9, v8
	s_nop 1
	v_permlane16_swap_b32_e32 v9, v8
	v_add_f32_e32 v8, v8, v9
	s_waitcnt vmcnt(14)
	v_pk_add_f32 v[14:15], v[14:15], 1.0 op_sel_hi:[1,0]
	v_pk_add_f32 v[16:17], v[16:17], 1.0 op_sel_hi:[1,0]
	s_nop 0
	v_lshl_add_u64 v[88:89], v[88:89], 0, s[16:17]
	s_waitcnt lgkmcnt(0)
	s_nop 1
	v_add_f32_dpp v8, v8, v8 row_mirror row_mask:0xf bank_mask:0xf
	s_nop 0
	v_readlane_b32 s16, v251, 28
	v_readlane_b32 s17, v251, 29
	s_waitcnt lgkmcnt(0)
	s_nop 1
	v_add_f32_dpp v8, v8, v8 row_half_mirror row_mask:0xf bank_mask:0xf
	s_nop 0
	v_lshl_add_u64 v[92:93], v[92:93], 0, s[16:17]
	s_waitcnt lgkmcnt(0)
	s_nop 1
	v_add_f32_dpp v24, v8, v8 quad_perm:[2,3,0,1] row_mask:0xf bank_mask:0xf
	v_lshlrev_b64 v[8:9], 12, v[108:109]
	v_lshl_add_u64 v[8:9], v[86:87], 0, v[8:9]
	s_nop 0
	s_waitcnt lgkmcnt(0)
	s_nop 1
	v_add_f32_dpp v24, v24, v24 quad_perm:[1,0,3,2] row_mask:0xf bank_mask:0xf
	v_fmamk_f32 v24, v24, 0x3a000000, v190
	v_mul_f32_e32 v25, 0x4b800000, v24
	v_cmp_gt_f32_e32 vcc, s79, v24
	s_nop 1
	v_cndmask_b32_e32 v24, v24, v25, vcc
	v_rsq_f32_e32 v28, v24
	s_nop 0
	v_mul_f32_e32 v29, 0x45800000, v28
	v_cndmask_b32_e32 v28, v28, v29, vcc
	v_pk_mul_f32 v[20:21], v[20:21], v[28:29] op_sel_hi:[1,0]
	v_pk_mul_f32 v[4:5], v[4:5], v[28:29] op_sel_hi:[1,0]
	v_pk_fma_f32 v[10:11], v[14:15], v[20:21], v[10:11]
	v_pk_mul_f32 v[14:15], v[22:23], v[28:29] op_sel_hi:[1,0]
	v_pk_mul_f32 v[22:23], v[26:27], v[28:29] op_sel_hi:[1,0]
	v_pk_fma_f32 v[12:13], v[16:17], v[14:15], v[12:13]
	v_bfe_u32 v16, v11, 16, 1
	v_bfe_u32 v17, v10, 16, 1
	v_add3_u32 v10, v10, v17, s94
	v_add3_u32 v16, v11, v16, s94
	v_cvt_pk_bf16_f32 v12, v12, v13
	v_mov_b32_e32 v11, v12
	v_perm_b32 v10, v16, v10, s95
	global_store_dwordx2 v[8:9], v[10:11], off
	s_nop 0
	s_nop 0
	s_nop 0
	s_nop 0
	v_pk_mul_f32 v[24:25], v[38:39], v[28:29] op_sel_hi:[1,0]
	v_pk_mul_f32 v[6:7], v[6:7], v[28:29] op_sel_hi:[1,0]
	v_cmp_lt_i32_e32 vcc, s15, v88
	s_or_b64 s[38:39], vcc, s[38:39]
	s_waitcnt vmcnt(14)
	v_pk_add_f32 v[10:11], v[206:207], 1.0 op_sel_hi:[1,0]
	s_waitcnt vmcnt(13)
	v_pk_fma_f32 v[10:11], v[10:11], v[22:23], v[210:211]
	v_pk_mul_f32 v[14:15], v[30:31], v[28:29] op_sel_hi:[1,0]
	v_pk_add_f32 v[12:13], v[208:209], 1.0 op_sel_hi:[1,0]
	v_pk_mul_f32 v[22:23], v[34:35], v[28:29] op_sel_hi:[1,0]
	v_pk_fma_f32 v[12:13], v[12:13], v[14:15], v[212:213]
	v_cvt_pk_bf16_f32 v12, v12, v13
	v_cvt_pk_bf16_f32 v10, v10, v11
	v_mov_b32_e32 v11, v12
	global_store_dwordx2 v[8:9], v[10:11], off offset:512
	s_nop 0
	s_nop 0
	s_nop 0
	s_nop 0
	s_waitcnt vmcnt(13)
	v_pk_add_f32 v[10:11], v[216:217], 1.0 op_sel_hi:[1,0]
	v_pk_add_f32 v[12:13], v[218:219], 1.0 op_sel_hi:[1,0]
	s_waitcnt vmcnt(12)
	v_pk_fma_f32 v[10:11], v[10:11], v[22:23], v[220:221]
	v_pk_fma_f32 v[12:13], v[12:13], v[24:25], v[222:223]
	v_cvt_pk_bf16_f32 v12, v12, v13
	v_cvt_pk_bf16_f32 v10, v10, v11
	v_mov_b32_e32 v11, v12
	global_store_dwordx2 v[8:9], v[10:11], off offset:1024
	s_nop 0
	s_nop 0
	s_nop 0
	v_pk_mul_f32 v[20:21], v[42:43], v[28:29] op_sel_hi:[1,0]
	v_pk_mul_f32 v[22:23], v[46:47], v[28:29] op_sel_hi:[1,0]
	s_nop 0
	s_waitcnt vmcnt(12)
	v_pk_add_f32 v[10:11], v[226:227], 1.0 op_sel_hi:[1,0]
	v_pk_add_f32 v[12:13], v[228:229], 1.0 op_sel_hi:[1,0]
	s_waitcnt vmcnt(11)
	v_pk_fma_f32 v[10:11], v[20:21], v[10:11], v[230:231]
	v_pk_fma_f32 v[12:13], v[22:23], v[12:13], v[232:233]
	v_cvt_pk_bf16_f32 v12, v12, v13
	v_cvt_pk_bf16_f32 v10, v10, v11
	v_mov_b32_e32 v11, v12
	global_store_dwordx2 v[8:9], v[10:11], off offset:1536
	s_nop 0
	s_nop 0
	s_nop 0
	v_pk_mul_f32 v[20:21], v[48:49], v[28:29] op_sel_hi:[1,0]
	v_pk_mul_f32 v[22:23], v[50:51], v[28:29] op_sel_hi:[1,0]
	s_nop 0
	s_waitcnt vmcnt(11)
	v_pk_add_f32 v[10:11], v[234:235], 1.0 op_sel_hi:[1,0]
	v_pk_add_f32 v[12:13], v[236:237], 1.0 op_sel_hi:[1,0]
	s_waitcnt vmcnt(10)
	v_pk_fma_f32 v[10:11], v[20:21], v[10:11], v[240:241]
	v_pk_fma_f32 v[12:13], v[22:23], v[12:13], v[242:243]
	v_cvt_pk_bf16_f32 v12, v12, v13
	v_cvt_pk_bf16_f32 v10, v10, v11
	v_mov_b32_e32 v11, v12
	global_store_dwordx2 v[8:9], v[10:11], off offset:2048
	s_nop 0
	s_nop 0
	s_nop 0
	v_pk_mul_f32 v[20:21], v[56:57], v[28:29] op_sel_hi:[1,0]
	v_pk_mul_f32 v[22:23], v[58:59], v[28:29] op_sel_hi:[1,0]
	s_nop 0
	s_nop 0
	s_waitcnt vmcnt(10)
	v_pk_add_f32 v[10:11], v[244:245], 1.0 op_sel_hi:[1,0]
	v_pk_add_f32 v[12:13], v[246:247], 1.0 op_sel_hi:[1,0]
	s_waitcnt vmcnt(9)
	v_pk_fma_f32 v[10:11], v[20:21], v[10:11], v[172:173]
	v_pk_fma_f32 v[12:13], v[22:23], v[12:13], v[174:175]
	v_cvt_pk_bf16_f32 v12, v12, v13
	v_cvt_pk_bf16_f32 v10, v10, v11
	v_mov_b32_e32 v11, v12
	global_store_dwordx2 v[8:9], v[10:11], off offset:2560
	s_nop 0
	s_nop 0
	s_nop 0
	v_pk_mul_f32 v[18:19], v[52:53], v[28:29] op_sel_hi:[1,0]
	v_pk_mul_f32 v[20:21], v[54:55], v[28:29] op_sel_hi:[1,0]
	s_nop 0
	s_waitcnt vmcnt(9)
	v_pk_add_f32 v[10:11], v[176:177], 1.0 op_sel_hi:[1,0]
	v_pk_add_f32 v[12:13], v[178:179], 1.0 op_sel_hi:[1,0]
	s_waitcnt vmcnt(8)
	v_pk_fma_f32 v[10:11], v[18:19], v[10:11], v[182:183]
	v_pk_fma_f32 v[12:13], v[20:21], v[12:13], v[184:185]
	v_cvt_pk_bf16_f32 v12, v12, v13
	v_cvt_pk_bf16_f32 v10, v10, v11
	v_mov_b32_e32 v11, v12
	global_store_dwordx2 v[8:9], v[10:11], off offset:3072
	s_nop 0
	s_waitcnt vmcnt(8)
	v_pk_add_f32 v[10:11], v[142:143], 1.0 op_sel_hi:[1,0]
	s_nop 0
	v_pk_add_f32 v[12:13], v[144:145], 1.0 op_sel_hi:[1,0]
	s_waitcnt vmcnt(7)
	v_pk_fma_f32 v[0:1], v[4:5], v[10:11], v[0:1]
	v_pk_fma_f32 v[2:3], v[6:7], v[12:13], v[2:3]
	v_cvt_pk_bf16_f32 v2, v2, v3
	v_cvt_pk_bf16_f32 v0, v0, v1
	v_mov_b32_e32 v1, v2
	global_store_dwordx2 v[8:9], v[0:1], off offset:3584
	v_mov_b32_e32 v14, v182
	v_mov_b32_e32 v15, v183
	v_mov_b32_e32 v16, v184
	v_mov_b32_e32 v17, v185
	s_andn2_b64 exec, exec, s[38:39]
	s_cbranch_execz .LBB0_437

.LBB0_433:
	s_mov_b64 s[40:41], -1
	s_and_b64 vcc, exec, s[72:73]
	s_cbranch_vccz .LBB0_435
	s_waitcnt vmcnt(7)
	v_add_f32_e32 v32, v1, v0
	v_add_f32_e32 v32, v2, v32
	s_waitcnt vmcnt(6)
	v_add_f32_e32 v33, v5, v4
	v_add_f32_e32 v32, v3, v32
	v_add_f32_e32 v33, v6, v33
	v_add_f32_e32 v32, 0, v32
	v_add_f32_e32 v33, v7, v33
	v_add_f32_e32 v32, v33, v32
	s_waitcnt vmcnt(5)
	v_add_f32_e32 v33, v9, v8
	v_add_f32_e32 v33, v10, v33
	v_add_f32_e32 v33, v11, v33
	v_add_f32_e32 v32, v33, v32
	s_waitcnt vmcnt(4)
	v_add_f32_e32 v33, v13, v12
	v_add_f32_e32 v33, v14, v33
	v_add_f32_e32 v33, v15, v33
	v_add_f32_e32 v36, v33, v32
	s_waitcnt vmcnt(2)
	v_mov_b32_e32 v32, v21
	v_mov_b32_e32 v33, v17
	v_mov_b32_e32 v34, v20
	v_mov_b32_e32 v35, v16
	v_pk_add_f32 v[32:33], v[32:33], v[34:35]
	v_mov_b32_e32 v34, v22
	v_mov_b32_e32 v35, v18
	v_pk_add_f32 v[32:33], v[34:35], v[32:33]
	v_mov_b32_e32 v34, v23
	v_mov_b32_e32 v35, v19
	v_pk_add_f32 v[32:33], v[34:35], v[32:33]
	s_waitcnt vmcnt(0)
	global_load_dwordx4 v[204:207], v[66:67], off
	global_load_dwordx4 v[208:211], v[68:69], off
	global_load_dwordx4 v[212:215], v[66:67], off offset:1024
	global_load_dwordx4 v[216:219], v[68:69], off offset:1024
	global_load_dwordx4 v[220:223], v[66:67], off offset:2048
	global_load_dwordx4 v[224:227], v[68:69], off offset:2048
	global_load_dwordx4 v[228:231], v[66:67], off offset:3072
	global_load_dwordx4 v[232:235], v[68:69], off offset:3072
	global_load_dwordx4 v[236:239], v[70:71], off
	global_load_dwordx4 v[240:243], v[72:73], off
	global_load_dwordx4 v[244:247], v[74:75], off
	global_load_dwordx4 v[172:175], v[76:77], off
	global_load_dwordx4 v[176:179], v[78:79], off
	global_load_dwordx4 v[180:183], v[80:81], off
	global_load_dwordx4 v[184:187], v[82:83], off
	global_load_dwordx4 v[142:145], v[84:85], off
	v_mov_b32_e32 v34, v28
	v_add_f32_e32 v33, v33, v36
	v_add_f32_e32 v36, v32, v33
	v_mov_b32_e32 v32, v29
	v_mov_b32_e32 v33, v25
	v_mov_b32_e32 v35, v24
	v_pk_add_f32 v[32:33], v[32:33], v[34:35]
	v_mov_b32_e32 v34, v30
	v_mov_b32_e32 v35, v26
	v_pk_add_f32 v[32:33], v[34:35], v[32:33]
	v_mov_b32_e32 v34, v31
	v_mov_b32_e32 v35, v27
	v_pk_add_f32 v[32:33], v[34:35], v[32:33]
	v_xor_b32_e32 v97, 32, v199
	v_add_f32_e32 v33, v33, v36
	v_add_f32_e32 v32, v32, v33
	v_and_b32_e32 v33, 64, v199
	v_add_u32_e32 v95, 64, v33
	v_cmp_lt_i32_e32 vcc, v97, v95
	v_xor_b32_e32 v99, 16, v199
	v_xor_b32_e32 v101, 8, v199
	v_cndmask_b32_e32 v33, v199, v97, vcc
	v_lshlrev_b32_e32 v136, 2, v33
	v_cmp_lt_i32_e32 vcc, v99, v95
	v_xor_b32_e32 v103, 4, v199
	v_xor_b32_e32 v105, 2, v199
	v_xor_b32_e32 v107, 1, v199
	s_waitcnt lgkmcnt(0)
	v_mov_b32_e32 v33, v32
	s_nop 1
	v_permlane32_swap_b32_e32 v33, v32
	v_add_f32_e32 v32, v32, v33
	v_cndmask_b32_e32 v33, v199, v99, vcc
	v_lshlrev_b32_e32 v137, 2, v33
	v_cmp_lt_i32_e32 vcc, v101, v95
	s_waitcnt lgkmcnt(0)
	v_mov_b32_e32 v33, v32
	s_nop 1
	v_permlane16_swap_b32_e32 v33, v32
	v_add_f32_e32 v32, v32, v33
	v_cndmask_b32_e32 v33, v199, v101, vcc
	v_lshlrev_b32_e32 v138, 2, v33
	v_cmp_lt_i32_e32 vcc, v103, v95
	s_waitcnt lgkmcnt(0)
	s_nop 1
	v_add_f32_dpp v32, v32, v32 row_mirror row_mask:0xf bank_mask:0xf
	v_cndmask_b32_e32 v33, v199, v103, vcc
	v_lshlrev_b32_e32 v139, 2, v33
	v_cmp_lt_i32_e32 vcc, v105, v95
	s_waitcnt lgkmcnt(0)
	s_nop 1
	v_add_f32_dpp v32, v32, v32 row_half_mirror row_mask:0xf bank_mask:0xf
	v_cndmask_b32_e32 v33, v199, v105, vcc
	v_lshlrev_b32_e32 v140, 2, v33
	v_cmp_lt_i32_e32 vcc, v107, v95
	s_waitcnt lgkmcnt(0)
	s_nop 1
	v_add_f32_dpp v32, v32, v32 quad_perm:[2,3,0,1] row_mask:0xf bank_mask:0xf
	v_cndmask_b32_e32 v33, v199, v107, vcc
	v_lshlrev_b32_e32 v141, 2, v33
	s_waitcnt lgkmcnt(0)
	s_nop 1
	v_add_f32_dpp v32, v32, v32 quad_perm:[1,0,3,2] row_mask:0xf bank_mask:0xf
	v_mul_f32_e32 v40, 0x3a000000, v32
	v_pk_add_f32 v[116:117], v[28:29], v[40:41] op_sel_hi:[1,0] neg_lo:[0,1] neg_hi:[0,1]
	v_pk_add_f32 v[110:111], v[24:25], v[40:41] op_sel_hi:[1,0] neg_lo:[0,1] neg_hi:[0,1]
	v_mov_b32_e32 v38, v117
	v_mov_b32_e32 v39, v111
	v_pk_add_f32 v[114:115], v[30:31], v[40:41] op_sel_hi:[1,0] neg_lo:[0,1] neg_hi:[0,1]
	v_pk_add_f32 v[108:109], v[26:27], v[40:41] op_sel_hi:[1,0] neg_lo:[0,1] neg_hi:[0,1]
	v_mov_b32_e32 v36, v116
	v_mov_b32_e32 v37, v110
	v_pk_mul_f32 v[38:39], v[38:39], v[38:39]
	v_pk_add_f32 v[62:63], v[20:21], v[40:41] op_sel_hi:[1,0] neg_lo:[0,1] neg_hi:[0,1]
	v_pk_add_f32 v[58:59], v[16:17], v[40:41] op_sel_hi:[1,0] neg_lo:[0,1] neg_hi:[0,1]
	v_mov_b32_e32 v32, v114
	v_mov_b32_e32 v33, v108
	v_pk_fma_f32 v[36:37], v[36:37], v[36:37], v[38:39]
	v_mov_b32_e32 v38, v63
	v_mov_b32_e32 v39, v59
	v_mov_b32_e32 v34, v115
	v_mov_b32_e32 v35, v109
	v_pk_fma_f32 v[32:33], v[32:33], v[32:33], v[36:37]
	v_pk_add_f32 v[60:61], v[22:23], v[40:41] op_sel_hi:[1,0] neg_lo:[0,1] neg_hi:[0,1]
	v_pk_add_f32 v[56:57], v[18:19], v[40:41] op_sel_hi:[1,0] neg_lo:[0,1] neg_hi:[0,1]
	v_mov_b32_e32 v36, v62
	v_mov_b32_e32 v37, v58
	v_pk_mul_f32 v[38:39], v[38:39], v[38:39]
	v_pk_fma_f32 v[42:43], v[34:35], v[34:35], v[32:33]
	v_mov_b32_e32 v32, v60
	v_mov_b32_e32 v33, v56
	v_pk_fma_f32 v[36:37], v[36:37], v[36:37], v[38:39]
	v_mov_b32_e32 v34, v61
	v_mov_b32_e32 v35, v57
	v_pk_fma_f32 v[32:33], v[32:33], v[32:33], v[36:37]
	v_pk_add_f32 v[126:127], v[4:5], v[40:41] op_sel_hi:[1,0] neg_lo:[0,1] neg_hi:[0,1]
	v_pk_fma_f32 v[44:45], v[34:35], v[34:35], v[32:33]
	s_nop 0
	s_nop 0
	v_pk_add_f32 v[122:123], v[6:7], v[40:41] op_sel_hi:[1,0] neg_lo:[0,1] neg_hi:[0,1]
	v_pk_mul_f32 v[128:129], v[126:127], v[126:127]
	v_pk_add_f32 v[52:53], v[14:15], v[40:41] op_sel_hi:[1,0] neg_lo:[0,1] neg_hi:[0,1]
	v_pk_add_f32 v[54:55], v[12:13], v[40:41] op_sel_hi:[1,0] neg_lo:[0,1] neg_hi:[0,1]
	v_pk_add_f32 v[50:51], v[10:11], v[40:41] op_sel_hi:[1,0] neg_lo:[0,1] neg_hi:[0,1]
	v_pk_add_f32 v[118:119], v[8:9], v[40:41] op_sel_hi:[1,0] neg_lo:[0,1] neg_hi:[0,1]
	v_pk_mul_f32 v[124:125], v[122:123], v[122:123]
	v_pk_add_f32 v[130:131], v[2:3], v[40:41] op_sel_hi:[1,0] neg_lo:[0,1] neg_hi:[0,1]
	v_pk_add_f32 v[40:41], v[0:1], v[40:41] op_sel_hi:[1,0] neg_lo:[0,1] neg_hi:[0,1]
	v_add_f32_e32 v128, v128, v129
	v_pk_mul_f32 v[134:135], v[40:41], v[40:41]
	v_add_f32_e32 v124, v124, v128
	v_pk_mul_f32 v[120:121], v[118:119], v[118:119]
	v_pk_mul_f32 v[132:133], v[130:131], v[130:131]
	v_add_f32_e32 v124, v125, v124
	v_add_f32_e32 v125, v134, v135
	v_pk_mul_f32 v[48:49], v[54:55], v[54:55]
	v_pk_mul_f32 v[112:113], v[50:51], v[50:51]
	v_add_f32_e32 v125, v132, v125
	v_add_f32_e32 v120, v120, v121
	v_pk_mul_f32 v[46:47], v[52:53], v[52:53]
	v_add_f32_e32 v125, v133, v125
	v_add_f32_e32 v112, v112, v120
	v_add_f32_e32 v48, v48, v49
	v_add_f32_e32 v124, v125, v124
	v_add_f32_e32 v112, v113, v112
	v_add_f32_e32 v46, v46, v48
	v_add_f32_e32 v112, v112, v124
	v_add_f32_e32 v46, v47, v46
	v_add_f32_e32 v46, v46, v112
	v_add_f32_e32 v45, v45, v46
	v_add_f32_e32 v44, v44, v45
	v_add_f32_e32 v43, v43, v44
	v_add_f32_e32 v42, v42, v43
	s_waitcnt lgkmcnt(0)
	v_mov_b32_e32 v43, v42
	s_nop 1
	v_permlane32_swap_b32_e32 v43, v42
	v_add_f32_e32 v42, v42, v43
	s_waitcnt lgkmcnt(0)
	v_mov_b32_e32 v43, v42
	s_nop 1
	v_permlane16_swap_b32_e32 v43, v42
	v_add_f32_e32 v42, v42, v43
	s_waitcnt lgkmcnt(0)
	s_nop 1
	v_add_f32_dpp v42, v42, v42 row_mirror row_mask:0xf bank_mask:0xf
	s_waitcnt lgkmcnt(0)
	s_nop 1
	v_add_f32_dpp v42, v42, v42 row_half_mirror row_mask:0xf bank_mask:0xf
	s_waitcnt lgkmcnt(0)
	s_nop 1
	v_add_f32_dpp v42, v42, v42 quad_perm:[2,3,0,1] row_mask:0xf bank_mask:0xf
	s_waitcnt lgkmcnt(0)
	s_nop 1
	v_add_f32_dpp v42, v42, v42 quad_perm:[1,0,3,2] row_mask:0xf bank_mask:0xf
	v_fmamk_f32 v42, v42, 0x3a000000, v190
	v_mul_f32_e32 v43, 0x4b800000, v42
	v_cmp_gt_f32_e32 vcc, s79, v42
	s_nop 1
	v_cndmask_b32_e32 v42, v42, v43, vcc
	v_rsq_f32_e32 v42, v42
	s_nop 0
	v_mul_f32_e32 v43, 0x45800000, v42
	v_cndmask_b32_e32 v120, v42, v43, vcc
	v_pk_mul_f32 v[40:41], v[40:41], v[120:121] op_sel_hi:[1,0]
	v_pk_mul_f32 v[44:45], v[126:127], v[120:121] op_sel_hi:[1,0]
	s_waitcnt vmcnt(14)
	v_pk_fma_f32 v[32:33], v[204:205], v[40:41], v[208:209]
	v_pk_mul_f32 v[36:37], v[130:131], v[120:121] op_sel_hi:[1,0]
	v_pk_mul_f32 v[46:47], v[122:123], v[120:121] op_sel_hi:[1,0]
	v_pk_fma_f32 v[34:35], v[206:207], v[36:37], v[210:211]
	global_store_dwordx4 v[92:93], v[32:35], off offset:-4096
	s_nop 0
	s_nop 0
	v_pk_mul_f32 v[48:49], v[118:119], v[120:121] op_sel_hi:[1,0]
	v_pk_mul_f32 v[50:51], v[50:51], v[120:121] op_sel_hi:[1,0]
	v_pk_mul_f32 v[54:55], v[54:55], v[120:121] op_sel_hi:[1,0]
	v_pk_mul_f32 v[52:53], v[52:53], v[120:121] op_sel_hi:[1,0]
	v_pk_mul_f32 v[58:59], v[58:59], v[120:121] op_sel_hi:[1,0]
	v_pk_mul_f32 v[56:57], v[56:57], v[120:121] op_sel_hi:[1,0]
	v_pk_mul_f32 v[62:63], v[62:63], v[120:121] op_sel_hi:[1,0]
	v_pk_mul_f32 v[60:61], v[60:61], v[120:121] op_sel_hi:[1,0]
	v_pk_mul_f32 v[110:111], v[110:111], v[120:121] op_sel_hi:[1,0]
	v_pk_mul_f32 v[108:109], v[108:109], v[120:121] op_sel_hi:[1,0]
	v_pk_mul_f32 v[116:117], v[116:117], v[120:121] op_sel_hi:[1,0]
	v_pk_mul_f32 v[114:115], v[114:115], v[120:121] op_sel_hi:[1,0]
	s_waitcnt vmcnt(13)
	v_pk_fma_f32 v[36:37], v[212:213], v[44:45], v[216:217]
	v_pk_fma_f32 v[38:39], v[214:215], v[46:47], v[218:219]
	global_store_dwordx4 v[92:93], v[36:39], off offset:-3072
	s_nop 0
	s_nop 0
	s_waitcnt vmcnt(12)
	v_pk_fma_f32 v[40:41], v[48:49], v[220:221], v[224:225]
	v_pk_fma_f32 v[42:43], v[50:51], v[222:223], v[226:227]
	global_store_dwordx4 v[92:93], v[40:43], off offset:-2048
	s_nop 0
	s_nop 0
	s_waitcnt vmcnt(11)
	v_pk_fma_f32 v[44:45], v[54:55], v[228:229], v[232:233]
	v_pk_fma_f32 v[46:47], v[52:53], v[230:231], v[234:235]
	global_store_dwordx4 v[92:93], v[44:47], off offset:-1024
	s_nop 0
	s_nop 0
	s_waitcnt vmcnt(10)
	v_pk_fma_f32 v[48:49], v[58:59], v[236:237], v[240:241]
	v_pk_fma_f32 v[50:51], v[56:57], v[238:239], v[242:243]
	global_store_dwordx4 v[92:93], v[48:51], off
	s_nop 0
	s_nop 0
	s_waitcnt vmcnt(9)
	v_pk_fma_f32 v[56:57], v[62:63], v[244:245], v[172:173]
	v_pk_fma_f32 v[58:59], v[60:61], v[246:247], v[174:175]
	global_store_dwordx4 v[92:93], v[56:59], off offset:1024
	s_nop 0
	s_nop 0
	s_waitcnt vmcnt(8)
	v_pk_fma_f32 v[52:53], v[110:111], v[176:177], v[180:181]
	v_pk_fma_f32 v[54:55], v[108:109], v[178:179], v[182:183]
	global_store_dwordx4 v[92:93], v[52:55], off offset:2048
	s_nop 0
	s_nop 0
	v_ashrrev_i32_e32 v109, 31, v88
	v_mov_b32_e32 v108, v88
	s_waitcnt vmcnt(7)
	v_pk_fma_f32 v[60:61], v[116:117], v[184:185], v[142:143]
	v_pk_fma_f32 v[62:63], v[114:115], v[186:187], v[144:145]
	global_store_dwordx4 v[92:93], v[60:63], off offset:3072
	v_mov_b32_e32 v110, v199
	v_mov_b32_e32 v111, v143
	v_mov_b32_e32 v112, v144
	v_mov_b32_e32 v113, v145
	s_cbranch_execnz .LBB0_428
	s_branch .LBB0_436

.LBB0_1050:
	global_load_dwordx2 v[52:53], v[40:41], off offset:-2048
	global_load_dwordx2 v[54:55], v[40:41], off offset:-1536
	global_load_dwordx2 v[56:57], v[40:41], off offset:-1024
	global_load_dwordx2 v[58:59], v[40:41], off offset:-512
	global_load_dwordx2 v[60:61], v[40:41], off
	global_load_dwordx2 v[62:63], v[40:41], off offset:512
	global_load_dwordx2 v[64:65], v[40:41], off offset:1024
	global_load_dwordx2 v[66:67], v[40:41], off offset:1536
	global_load_dwordx4 v[0:3], v[8:9], off
	global_load_dwordx4 v[4:7], v[10:11], off
	v_add_u32_e32 v44, s8, v44
	v_lshl_add_u64 v[40:41], v[40:41], 0, s[10:11]
	global_load_dwordx4 v[204:207], v[12:13], off
	global_load_dwordx4 v[208:211], v[14:15], off
	global_load_dwordx4 v[212:215], v[16:17], off
	global_load_dwordx4 v[216:219], v[18:19], off
	global_load_dwordx4 v[220:223], v[20:21], off
	global_load_dwordx4 v[224:227], v[22:23], off
	global_load_dwordx4 v[228:231], v[24:25], off
	global_load_dwordx4 v[232:235], v[26:27], off
	global_load_dwordx4 v[236:239], v[28:29], off
	global_load_dwordx4 v[240:243], v[30:31], off
	global_load_dwordx4 v[244:247], v[32:33], off
	global_load_dwordx4 v[172:175], v[34:35], off
	global_load_dwordx4 v[176:179], v[36:37], off
	global_load_dwordx4 v[180:183], v[38:39], off
	s_waitcnt vmcnt(23)
	v_and_b32_e32 v69, 0xffff0000, v52
	v_lshlrev_b32_e32 v68, 16, v52
	v_and_b32_e32 v71, 0xffff0000, v53
	v_lshlrev_b32_e32 v70, 16, v53
	s_waitcnt vmcnt(22)
	v_and_b32_e32 v53, 0xffff0000, v54
	v_lshlrev_b32_e32 v52, 16, v54
	v_and_b32_e32 v73, 0xffff0000, v55
	v_lshlrev_b32_e32 v72, 16, v55
	s_waitcnt vmcnt(21)
	v_and_b32_e32 v55, 0xffff0000, v56
	v_lshlrev_b32_e32 v54, 16, v56
	v_and_b32_e32 v75, 0xffff0000, v57
	v_lshlrev_b32_e32 v74, 16, v57
	s_waitcnt vmcnt(20)
	v_and_b32_e32 v57, 0xffff0000, v58
	v_lshlrev_b32_e32 v56, 16, v58
	v_and_b32_e32 v77, 0xffff0000, v59
	v_lshlrev_b32_e32 v76, 16, v59
	s_waitcnt vmcnt(19)
	v_and_b32_e32 v59, 0xffff0000, v60
	v_lshlrev_b32_e32 v58, 16, v60
	v_and_b32_e32 v79, 0xffff0000, v61
	v_lshlrev_b32_e32 v78, 16, v61
	s_waitcnt vmcnt(18)
	v_and_b32_e32 v61, 0xffff0000, v62
	v_lshlrev_b32_e32 v60, 16, v62
	v_and_b32_e32 v81, 0xffff0000, v63
	v_lshlrev_b32_e32 v80, 16, v63
	s_waitcnt vmcnt(17)
	v_and_b32_e32 v63, 0xffff0000, v64
	v_lshlrev_b32_e32 v62, 16, v64
	v_and_b32_e32 v83, 0xffff0000, v65
	v_lshlrev_b32_e32 v82, 16, v65
	s_waitcnt vmcnt(16)
	v_and_b32_e32 v65, 0xffff0000, v66
	v_lshlrev_b32_e32 v64, 16, v66
	v_add_f32_e32 v100, v69, v68
	v_and_b32_e32 v85, 0xffff0000, v67
	v_lshlrev_b32_e32 v84, 16, v67
	v_add_f32_e32 v101, v53, v52
	v_mov_b32_e32 v66, v58
	v_mov_b32_e32 v67, v60
	v_mov_b32_e32 v86, v59
	v_mov_b32_e32 v87, v61
	v_mov_b32_e32 v92, v62
	v_mov_b32_e32 v93, v64
	v_mov_b32_e32 v94, v63
	v_mov_b32_e32 v95, v65
	v_add_f32_e32 v100, v100, v70
	v_add_f32_e32 v102, v55, v54
	v_mov_b32_e32 v88, v78
	v_mov_b32_e32 v89, v80
	v_add_f32_e32 v101, v101, v72
	v_pk_add_f32 v[66:67], v[66:67], v[86:87]
	v_pk_add_f32 v[86:87], v[92:93], v[94:95]
	v_add_f32_e32 v92, v100, v71
	v_add_f32_e32 v103, v57, v56
	v_add_f32_e32 v102, v102, v74
	v_add_f32_e32 v93, v101, v73
	v_pk_add_f32 v[66:67], v[66:67], v[88:89]
	v_add_f32_e32 v88, 0, v92
	v_add_f32_e32 v103, v103, v76
	v_add_f32_e32 v94, v102, v75
	v_add_f32_e32 v88, v88, v93
	v_mov_b32_e32 v90, v79
	v_mov_b32_e32 v91, v81
	v_add_f32_e32 v95, v103, v77
	v_add_f32_e32 v88, v88, v94
	v_mov_b32_e32 v96, v82
	v_mov_b32_e32 v97, v84
	v_pk_add_f32 v[66:67], v[66:67], v[90:91]
	v_add_f32_e32 v88, v88, v95
	v_mov_b32_e32 v98, v83
	v_mov_b32_e32 v99, v85
	v_pk_add_f32 v[86:87], v[86:87], v[96:97]
	v_add_f32_e32 v66, v88, v66
	v_pk_add_f32 v[86:87], v[86:87], v[98:99]
	v_add_f32_e32 v66, v66, v67
	v_add_f32_e32 v66, v66, v86
	v_add_f32_e32 v66, v66, v87
	s_waitcnt lgkmcnt(0)
	v_mov_b32_e32 v67, v66
	s_nop 1
	v_permlane32_swap_b32_e32 v67, v66
	v_add_f32_e32 v66, v66, v67
	s_waitcnt lgkmcnt(0)
	v_mov_b32_e32 v67, v66
	s_nop 1
	v_permlane16_swap_b32_e32 v67, v66
	v_add_f32_e32 v66, v66, v67
	s_waitcnt lgkmcnt(0)
	s_nop 1
	v_add_f32_dpp v66, v66, v66 row_mirror row_mask:0xf bank_mask:0xf
	s_waitcnt lgkmcnt(0)
	s_nop 1
	v_add_f32_dpp v66, v66, v66 row_half_mirror row_mask:0xf bank_mask:0xf
	s_waitcnt lgkmcnt(0)
	s_nop 1
	v_add_f32_dpp v66, v66, v66 quad_perm:[2,3,0,1] row_mask:0xf bank_mask:0xf
	s_waitcnt lgkmcnt(0)
	s_nop 1
	v_add_f32_dpp v66, v66, v66 quad_perm:[1,0,3,2] row_mask:0xf bank_mask:0xf
	v_mul_f32_e32 v66, 0x3a000000, v66
	v_pk_add_f32 v[68:69], v[68:69], v[66:67] op_sel_hi:[1,0] neg_lo:[0,1] neg_hi:[0,1]
	v_pk_add_f32 v[52:53], v[52:53], v[66:67] op_sel_hi:[1,0] neg_lo:[0,1] neg_hi:[0,1]
	v_pk_add_f32 v[62:63], v[62:63], v[66:67] op_sel_hi:[1,0] neg_lo:[0,1] neg_hi:[0,1]
	v_pk_add_f32 v[64:65], v[64:65], v[66:67] op_sel_hi:[1,0] neg_lo:[0,1] neg_hi:[0,1]
	v_pk_add_f32 v[70:71], v[70:71], v[66:67] op_sel_hi:[1,0] neg_lo:[0,1] neg_hi:[0,1]
	v_pk_add_f32 v[72:73], v[72:73], v[66:67] op_sel_hi:[1,0] neg_lo:[0,1] neg_hi:[0,1]
	v_pk_add_f32 v[54:55], v[54:55], v[66:67] op_sel_hi:[1,0] neg_lo:[0,1] neg_hi:[0,1]
	v_pk_add_f32 v[74:75], v[74:75], v[66:67] op_sel_hi:[1,0] neg_lo:[0,1] neg_hi:[0,1]
	v_pk_add_f32 v[56:57], v[56:57], v[66:67] op_sel_hi:[1,0] neg_lo:[0,1] neg_hi:[0,1]
	v_pk_add_f32 v[76:77], v[76:77], v[66:67] op_sel_hi:[1,0] neg_lo:[0,1] neg_hi:[0,1]
	v_pk_add_f32 v[58:59], v[58:59], v[66:67] op_sel_hi:[1,0] neg_lo:[0,1] neg_hi:[0,1]
	v_pk_add_f32 v[78:79], v[78:79], v[66:67] op_sel_hi:[1,0] neg_lo:[0,1] neg_hi:[0,1]
	v_pk_add_f32 v[60:61], v[60:61], v[66:67] op_sel_hi:[1,0] neg_lo:[0,1] neg_hi:[0,1]
	v_pk_add_f32 v[80:81], v[80:81], v[66:67] op_sel_hi:[1,0] neg_lo:[0,1] neg_hi:[0,1]
	v_pk_add_f32 v[82:83], v[82:83], v[66:67] op_sel_hi:[1,0] neg_lo:[0,1] neg_hi:[0,1]
	v_pk_add_f32 v[66:67], v[84:85], v[66:67] op_sel_hi:[1,0] neg_lo:[0,1] neg_hi:[0,1]
	v_pk_mul_f32 v[84:85], v[68:69], v[68:69]
	v_pk_mul_f32 v[88:89], v[52:53], v[52:53]
	v_mov_b32_e32 v110, v65
	v_mov_b32_e32 v111, v63
	v_pk_mul_f32 v[86:87], v[70:71], v[70:71]
	v_pk_mul_f32 v[90:91], v[72:73], v[72:73]
	v_pk_mul_f32 v[92:93], v[54:55], v[54:55]
	v_mov_b32_e32 v108, v64
	v_mov_b32_e32 v109, v62
	v_pk_mul_f32 v[110:111], v[110:111], v[110:111]
	v_add_f32_e32 v116, v88, v89
	v_add_f32_e32 v117, v84, v85
	v_pk_mul_f32 v[94:95], v[74:75], v[74:75]
	v_pk_mul_f32 v[96:97], v[56:57], v[56:57]
	v_mov_b32_e32 v102, v61
	v_mov_b32_e32 v103, v59
	v_mov_b32_e32 v112, v66
	v_mov_b32_e32 v113, v82
	v_add_f32_e32 v92, v92, v93
	v_pk_fma_f32 v[88:89], v[108:109], v[108:109], v[110:111]
	v_add_f32_e32 v90, v90, v116
	v_add_f32_e32 v86, v86, v117
	v_pk_mul_f32 v[98:99], v[76:77], v[76:77]
	v_mov_b32_e32 v100, v60
	v_mov_b32_e32 v101, v58
	v_mov_b32_e32 v114, v67
	v_mov_b32_e32 v115, v83
	v_pk_mul_f32 v[102:103], v[102:103], v[102:103]
	v_add_f32_e32 v93, v96, v97
	v_add_f32_e32 v92, v94, v92
	v_pk_fma_f32 v[88:89], v[112:113], v[112:113], v[88:89]
	v_add_f32_e32 v90, v91, v90
	v_add_f32_e32 v91, v87, v86
	v_mov_b32_e32 v104, v80
	v_mov_b32_e32 v105, v78
	v_pk_fma_f32 v[84:85], v[100:101], v[100:101], v[102:103]
	v_add_f32_e32 v93, v98, v93
	v_add_f32_e32 v92, v95, v92
	v_pk_fma_f32 v[86:87], v[114:115], v[114:115], v[88:89]
	v_add_f32_e32 v88, v91, v90
	v_mov_b32_e32 v106, v81
	v_mov_b32_e32 v107, v79
	v_pk_fma_f32 v[84:85], v[104:105], v[104:105], v[84:85]
	v_add_f32_e32 v93, v99, v93
	v_add_f32_e32 v88, v92, v88
	v_pk_fma_f32 v[84:85], v[106:107], v[106:107], v[84:85]
	v_add_f32_e32 v88, v93, v88
	v_add_f32_e32 v85, v85, v88
	v_add_f32_e32 v84, v84, v85
	v_add_f32_e32 v84, v87, v84
	v_add_f32_e32 v84, v86, v84
	s_waitcnt lgkmcnt(0)
	v_mov_b32_e32 v85, v84
	s_nop 1
	v_permlane32_swap_b32_e32 v85, v84
	v_add_f32_e32 v84, v84, v85
	s_waitcnt lgkmcnt(0)
	v_mov_b32_e32 v85, v84
	s_nop 1
	v_permlane16_swap_b32_e32 v85, v84
	v_add_f32_e32 v84, v84, v85
	s_waitcnt lgkmcnt(0)
	s_nop 1
	v_add_f32_dpp v84, v84, v84 row_mirror row_mask:0xf bank_mask:0xf
	s_waitcnt lgkmcnt(0)
	s_nop 1
	v_add_f32_dpp v84, v84, v84 row_half_mirror row_mask:0xf bank_mask:0xf
	s_waitcnt lgkmcnt(0)
	s_nop 1
	v_add_f32_dpp v84, v84, v84 quad_perm:[2,3,0,1] row_mask:0xf bank_mask:0xf
	s_waitcnt lgkmcnt(0)
	s_nop 1
	v_add_f32_dpp v84, v84, v84 quad_perm:[1,0,3,2] row_mask:0xf bank_mask:0xf
	v_fmamk_f32 v84, v84, 0x3a000000, v51
	v_mul_f32_e32 v85, 0x4b800000, v84
	v_cmp_gt_f32_e32 vcc, s2, v84
	s_nop 1
	v_cndmask_b32_e32 v84, v84, v85, vcc
	v_rsq_f32_e32 v84, v84
	s_nop 0
	v_mul_f32_e32 v85, 0x45800000, v84
	v_cndmask_b32_e32 v84, v84, v85, vcc
	v_pk_mul_f32 v[68:69], v[68:69], v[84:85] op_sel_hi:[1,0]
	v_pk_mul_f32 v[70:71], v[70:71], v[84:85] op_sel_hi:[1,0]
	s_waitcnt vmcnt(14)
	v_pk_fma_f32 v[0:1], v[0:1], v[68:69], v[4:5]
	v_pk_fma_f32 v[2:3], v[2:3], v[70:71], v[6:7]
	global_store_dwordx4 v[42:43], v[0:3], off offset:-4096
	s_nop 0
	s_nop 0
	s_nop 0
	v_pk_mul_f32 v[52:53], v[52:53], v[84:85] op_sel_hi:[1,0]
	v_pk_mul_f32 v[68:69], v[72:73], v[84:85] op_sel_hi:[1,0]
	v_cmp_lt_i32_e32 vcc, s3, v44
	s_or_b64 s[0:1], vcc, s[0:1]
	s_waitcnt vmcnt(13)
	v_pk_fma_f32 v[0:1], v[204:205], v[52:53], v[208:209]
	v_pk_fma_f32 v[2:3], v[206:207], v[68:69], v[210:211]
	global_store_dwordx4 v[42:43], v[0:3], off offset:-3072
	s_nop 0
	s_nop 0
	s_nop 0
	v_pk_mul_f32 v[52:53], v[54:55], v[84:85] op_sel_hi:[1,0]
	v_pk_mul_f32 v[54:55], v[74:75], v[84:85] op_sel_hi:[1,0]
	s_waitcnt vmcnt(12)
	v_pk_fma_f32 v[0:1], v[212:213], v[52:53], v[216:217]
	v_pk_fma_f32 v[2:3], v[214:215], v[54:55], v[218:219]
	global_store_dwordx4 v[42:43], v[0:3], off offset:-2048
	s_nop 0
	s_nop 0
	s_nop 0
	v_pk_mul_f32 v[52:53], v[56:57], v[84:85] op_sel_hi:[1,0]
	v_pk_mul_f32 v[54:55], v[76:77], v[84:85] op_sel_hi:[1,0]
	s_waitcnt vmcnt(11)
	v_pk_fma_f32 v[0:1], v[52:53], v[220:221], v[224:225]
	v_pk_fma_f32 v[2:3], v[54:55], v[222:223], v[226:227]
	global_store_dwordx4 v[42:43], v[0:3], off offset:-1024
	s_nop 0
	s_nop 0
	s_nop 0
	v_pk_mul_f32 v[52:53], v[58:59], v[84:85] op_sel_hi:[1,0]
	v_pk_mul_f32 v[54:55], v[78:79], v[84:85] op_sel_hi:[1,0]
	s_waitcnt vmcnt(10)
	v_pk_fma_f32 v[0:1], v[52:53], v[228:229], v[232:233]
	v_pk_fma_f32 v[2:3], v[54:55], v[230:231], v[234:235]
	global_store_dwordx4 v[42:43], v[0:3], off
	s_nop 0
	s_nop 0
	s_nop 0
	v_pk_mul_f32 v[52:53], v[60:61], v[84:85] op_sel_hi:[1,0]
	v_pk_mul_f32 v[54:55], v[80:81], v[84:85] op_sel_hi:[1,0]
	s_waitcnt vmcnt(9)
	v_pk_fma_f32 v[0:1], v[52:53], v[236:237], v[240:241]
	v_pk_fma_f32 v[2:3], v[54:55], v[238:239], v[242:243]
	global_store_dwordx4 v[42:43], v[0:3], off offset:1024
	s_nop 0
	s_nop 0
	s_nop 0
	v_pk_mul_f32 v[52:53], v[62:63], v[84:85] op_sel_hi:[1,0]
	v_pk_mul_f32 v[54:55], v[82:83], v[84:85] op_sel_hi:[1,0]
	s_waitcnt vmcnt(8)
	v_pk_fma_f32 v[0:1], v[52:53], v[244:245], v[172:173]
	v_pk_fma_f32 v[2:3], v[54:55], v[246:247], v[174:175]
	global_store_dwordx4 v[42:43], v[0:3], off offset:2048
	s_nop 0
	s_nop 0
	s_nop 0
	v_pk_mul_f32 v[52:53], v[64:65], v[84:85] op_sel_hi:[1,0]
	v_pk_mul_f32 v[54:55], v[66:67], v[84:85] op_sel_hi:[1,0]
	s_waitcnt vmcnt(7)
	v_pk_fma_f32 v[0:1], v[52:53], v[176:177], v[180:181]
	v_pk_fma_f32 v[2:3], v[54:55], v[178:179], v[182:183]
	global_store_dwordx4 v[42:43], v[0:3], off offset:3072
	v_lshl_add_u64 v[42:43], v[42:43], 0, s[12:13]
	v_mov_b32_e32 v4, v180
	v_mov_b32_e32 v5, v181
	v_mov_b32_e32 v6, v182
	v_mov_b32_e32 v7, v183
	s_andn2_b64 exec, exec, s[0:1]
	s_cbranch_execnz .LBB0_1050
